# ctx units on RG workgroups + gate/up GEMM K-loop LDS-DMA addresses in saddr form
# speedup vs baseline: 1.0005x; 1.0005x over previous
.LBB0_1248:
	s_add_u32 s22, s20, 0xfffc0080
	s_addc_u32 s23, s21, -1
	s_add_i32 s48, 0, 0x10000
	s_cmp_eq_u32 s47, 12
	s_cselect_b32 s25, s13, s23
	s_cselect_b32 s24, s19, s22
	s_cselect_b32 s23, s11, s46
	s_cselect_b32 s22, s44, s45
	s_add_i32 s50, 0, 0x14000
	v_add_u32_e32 v142, s48, v171
	v_add_u32_e32 v164, s50, v171
	ds_read_b128 v[130:133], v142
	ds_read_b128 v[134:137], v142 offset:1024
	ds_read_b128 v[138:141], v142 offset:2048
	ds_read_b128 v[142:145], v142 offset:3072
	ds_read_b128 v[160:163], v164
	ds_read_b128 v[176:179], v164 offset:1024
	ds_read_b128 v[180:183], v164 offset:2048
	ds_read_b128 v[184:187], v164 offset:3072
	s_add_i32 m0, s31, 0xc000
	ds_read_b128 v[188:191], v175
	ds_read_b128 v[192:195], v175 offset:1024
	ds_read_b128 v[196:199], v175 offset:2048
	ds_read_b128 v[200:203], v175 offset:3072
	ds_read_b128 v[204:207], v175 offset:4096
	ds_read_b128 v[208:211], v175 offset:5120
	ds_read_b128 v[212:215], v175 offset:6144
	ds_read_b128 v[216:219], v175 offset:7168
	global_load_lds_dwordx4 v156, s[20:21]
	s_add_i32 m0, s31, 0xe000
	s_nop 0
	global_load_lds_dwordx4 v158, s[20:21]
	s_waitcnt vmcnt(8)
	s_waitcnt lgkmcnt(0)
	s_barrier
	s_setprio 1
	s_waitcnt lgkmcnt(0)
	v_mfma_f32_16x16x32_bf16 v[126:129], v[130:133], v[188:191], v[126:129]
	v_mfma_f32_16x16x32_bf16 v[122:125], v[138:141], v[188:191], v[122:125]
	v_mfma_f32_16x16x32_bf16 v[110:113], v[130:133], v[196:199], v[110:113]
	v_mfma_f32_16x16x32_bf16 v[106:109], v[138:141], v[196:199], v[106:109]
	v_mfma_f32_16x16x32_bf16 v[94:97], v[130:133], v[204:207], v[94:97]
	v_mfma_f32_16x16x32_bf16 v[90:93], v[138:141], v[204:207], v[90:93]
	v_mfma_f32_16x16x32_bf16 v[78:81], v[130:133], v[212:215], v[78:81]
	v_mfma_f32_16x16x32_bf16 v[74:77], v[138:141], v[212:215], v[74:77]
	v_mfma_f32_16x16x32_bf16 v[126:129], v[134:137], v[192:195], v[126:129]
	v_mfma_f32_16x16x32_bf16 v[122:125], v[142:145], v[192:195], v[122:125]
	v_mfma_f32_16x16x32_bf16 v[110:113], v[134:137], v[200:203], v[110:113]
	v_mfma_f32_16x16x32_bf16 v[106:109], v[142:145], v[200:203], v[106:109]
	v_mfma_f32_16x16x32_bf16 v[94:97], v[134:137], v[208:211], v[94:97]
	v_mfma_f32_16x16x32_bf16 v[90:93], v[142:145], v[208:211], v[90:93]
	v_mfma_f32_16x16x32_bf16 v[78:81], v[134:137], v[216:219], v[78:81]
	v_mfma_f32_16x16x32_bf16 v[74:77], v[142:145], v[216:219], v[74:77]
	s_setprio 0
	s_setprio 1
	v_mfma_f32_16x16x32_bf16 v[118:121], v[160:163], v[188:191], v[118:121]
	v_mfma_f32_16x16x32_bf16 v[114:117], v[180:183], v[188:191], v[114:117]
	v_mfma_f32_16x16x32_bf16 v[102:105], v[160:163], v[196:199], v[102:105]
	v_mfma_f32_16x16x32_bf16 v[98:101], v[180:183], v[196:199], v[98:101]
	v_mfma_f32_16x16x32_bf16 v[86:89], v[160:163], v[204:207], v[86:89]
	v_mfma_f32_16x16x32_bf16 v[82:85], v[180:183], v[204:207], v[82:85]
	v_mfma_f32_16x16x32_bf16 v[70:73], v[160:163], v[212:215], v[70:73]
	v_mfma_f32_16x16x32_bf16 v[66:69], v[180:183], v[212:215], v[66:69]
	v_mfma_f32_16x16x32_bf16 v[118:121], v[176:179], v[192:195], v[118:121]
	v_mfma_f32_16x16x32_bf16 v[114:117], v[184:187], v[192:195], v[114:117]
	v_mfma_f32_16x16x32_bf16 v[102:105], v[176:179], v[200:203], v[102:105]
	v_mfma_f32_16x16x32_bf16 v[98:101], v[184:187], v[200:203], v[98:101]
	v_mfma_f32_16x16x32_bf16 v[86:89], v[176:179], v[208:211], v[86:89]
	v_mfma_f32_16x16x32_bf16 v[82:85], v[184:187], v[208:211], v[82:85]
	v_mfma_f32_16x16x32_bf16 v[70:73], v[176:179], v[216:219], v[70:73]
	v_mfma_f32_16x16x32_bf16 v[66:69], v[184:187], v[216:219], v[66:69]
	s_setprio 0
	s_barrier
	s_add_i32 s48, s48, s30
	s_add_u32 s98, s22, 0x80
	s_addc_u32 s99, s23, 0
	s_mov_b32 m0, s48
	ds_read_b128 v[188:191], v175 offset:16384
	ds_read_b128 v[192:195], v175 offset:17408
	ds_read_b128 v[196:199], v175 offset:18432
	ds_read_b128 v[200:203], v175 offset:19456
	ds_read_b128 v[204:207], v175 offset:20480
	ds_read_b128 v[208:211], v175 offset:21504
	ds_read_b128 v[212:215], v175 offset:22528
	ds_read_b128 v[216:219], v175 offset:23552
	global_load_lds_dwordx4 v0, s[22:23]
	s_add_i32 m0, s48, 0x2000
	s_add_u32 s48, s22, 0x40000
	s_addc_u32 s49, s23, 0
	s_add_i32 s50, s50, s30
	global_load_lds_dwordx4 v146, s[22:23]
	s_mov_b32 m0, s50
	s_add_u32 s100, s24, 0x80
	s_addc_u32 s101, s25, 0
	global_load_lds_dwordx4 v0, s[48:49]
	s_add_i32 m0, s50, 0x2000
	s_nop 0
	global_load_lds_dwordx4 v146, s[48:49]
	s_mov_b32 m0, s31
	s_nop 0
	global_load_lds_dwordx4 v150, s[24:25]
	s_mov_b32 m0, s33
	s_nop 0
	global_load_lds_dwordx4 v148, s[24:25]
	s_waitcnt vmcnt(8)
	s_waitcnt lgkmcnt(0)
	s_barrier
	s_setprio 1
	s_waitcnt lgkmcnt(0)
	v_mfma_f32_16x16x32_bf16 v[62:65], v[130:133], v[188:191], v[62:65]
	v_mfma_f32_16x16x32_bf16 v[58:61], v[138:141], v[188:191], v[58:61]
	v_mfma_f32_16x16x32_bf16 v[46:49], v[130:133], v[196:199], v[46:49]
	v_mfma_f32_16x16x32_bf16 v[42:45], v[138:141], v[196:199], v[42:45]
	v_mfma_f32_16x16x32_bf16 v[30:33], v[130:133], v[204:207], v[30:33]
	v_mfma_f32_16x16x32_bf16 v[26:29], v[138:141], v[204:207], v[26:29]
	v_mfma_f32_16x16x32_bf16 v[14:17], v[130:133], v[212:215], v[14:17]
	v_mfma_f32_16x16x32_bf16 v[10:13], v[138:141], v[212:215], v[10:13]
	v_mfma_f32_16x16x32_bf16 v[62:65], v[134:137], v[192:195], v[62:65]
	v_mfma_f32_16x16x32_bf16 v[58:61], v[142:145], v[192:195], v[58:61]
	v_mfma_f32_16x16x32_bf16 v[46:49], v[134:137], v[200:203], v[46:49]
	v_mfma_f32_16x16x32_bf16 v[42:45], v[142:145], v[200:203], v[42:45]
	v_mfma_f32_16x16x32_bf16 v[30:33], v[134:137], v[208:211], v[30:33]
	v_mfma_f32_16x16x32_bf16 v[26:29], v[142:145], v[208:211], v[26:29]
	v_mfma_f32_16x16x32_bf16 v[14:17], v[134:137], v[216:219], v[14:17]
	v_mfma_f32_16x16x32_bf16 v[10:13], v[142:145], v[216:219], v[10:13]
	s_setprio 0
	s_setprio 1
	v_mfma_f32_16x16x32_bf16 v[54:57], v[160:163], v[188:191], v[54:57]
	v_mfma_f32_16x16x32_bf16 v[50:53], v[180:183], v[188:191], v[50:53]
	v_mfma_f32_16x16x32_bf16 v[38:41], v[160:163], v[196:199], v[38:41]
	v_mfma_f32_16x16x32_bf16 v[34:37], v[180:183], v[196:199], v[34:37]
	v_mfma_f32_16x16x32_bf16 v[22:25], v[160:163], v[204:207], v[22:25]
	v_mfma_f32_16x16x32_bf16 v[18:21], v[180:183], v[204:207], v[18:21]
	v_mfma_f32_16x16x32_bf16 v[6:9], v[160:163], v[212:215], v[6:9]
	v_mfma_f32_16x16x32_bf16 v[2:5], v[180:183], v[212:215], v[2:5]
	v_mfma_f32_16x16x32_bf16 v[54:57], v[176:179], v[192:195], v[54:57]
	v_mfma_f32_16x16x32_bf16 v[50:53], v[184:187], v[192:195], v[50:53]
	v_mfma_f32_16x16x32_bf16 v[38:41], v[176:179], v[200:203], v[38:41]
	v_mfma_f32_16x16x32_bf16 v[34:37], v[184:187], v[200:203], v[34:37]
	v_mfma_f32_16x16x32_bf16 v[22:25], v[176:179], v[208:211], v[22:25]
	v_mfma_f32_16x16x32_bf16 v[18:21], v[184:187], v[208:211], v[18:21]
	v_mfma_f32_16x16x32_bf16 v[6:9], v[176:179], v[216:219], v[6:9]
	v_mfma_f32_16x16x32_bf16 v[2:5], v[184:187], v[216:219], v[2:5]
	s_setprio 0
	s_barrier
	s_add_i32 s48, 0, 0x18000
	s_add_i32 s49, 0, 0x1c000
	v_add_u32_e32 v142, s48, v171
	v_add_u32_e32 v166, s49, v171
	ds_read_b128 v[130:133], v142
	ds_read_b128 v[134:137], v142 offset:1024
	ds_read_b128 v[138:141], v142 offset:2048
	ds_read_b128 v[142:145], v142 offset:3072
	ds_read_b128 v[160:163], v166
	ds_read_b128 v[176:179], v166 offset:1024
	ds_read_b128 v[180:183], v166 offset:2048
	ds_read_b128 v[184:187], v166 offset:3072
	s_add_u32 s24, s24, 0x40000
	s_addc_u32 s25, s25, 0
	s_mov_b32 m0, s34
	ds_read_b128 v[188:191], v175 offset:32768
	ds_read_b128 v[192:195], v175 offset:33792
	ds_read_b128 v[196:199], v175 offset:34816
	ds_read_b128 v[200:203], v175 offset:35840
	ds_read_b128 v[204:207], v175 offset:36864
	ds_read_b128 v[208:211], v175 offset:37888
	ds_read_b128 v[212:215], v175 offset:38912
	ds_read_b128 v[216:219], v175 offset:39936
	global_load_lds_dwordx4 v150, s[24:25]
	s_mov_b32 m0, s35
	s_nop 0
	global_load_lds_dwordx4 v148, s[24:25]
	s_waitcnt vmcnt(8)
	s_waitcnt lgkmcnt(0)
	s_barrier
	s_setprio 1
	s_waitcnt lgkmcnt(0)
	v_mfma_f32_16x16x32_bf16 v[126:129], v[130:133], v[188:191], v[126:129]
	v_mfma_f32_16x16x32_bf16 v[122:125], v[138:141], v[188:191], v[122:125]
	v_mfma_f32_16x16x32_bf16 v[110:113], v[130:133], v[196:199], v[110:113]
	v_mfma_f32_16x16x32_bf16 v[106:109], v[138:141], v[196:199], v[106:109]
	v_mfma_f32_16x16x32_bf16 v[94:97], v[130:133], v[204:207], v[94:97]
	v_mfma_f32_16x16x32_bf16 v[90:93], v[138:141], v[204:207], v[90:93]
	v_mfma_f32_16x16x32_bf16 v[78:81], v[130:133], v[212:215], v[78:81]
	v_mfma_f32_16x16x32_bf16 v[74:77], v[138:141], v[212:215], v[74:77]
	v_mfma_f32_16x16x32_bf16 v[126:129], v[134:137], v[192:195], v[126:129]
	v_mfma_f32_16x16x32_bf16 v[122:125], v[142:145], v[192:195], v[122:125]
	v_mfma_f32_16x16x32_bf16 v[110:113], v[134:137], v[200:203], v[110:113]
	v_mfma_f32_16x16x32_bf16 v[106:109], v[142:145], v[200:203], v[106:109]
	v_mfma_f32_16x16x32_bf16 v[94:97], v[134:137], v[208:211], v[94:97]
	v_mfma_f32_16x16x32_bf16 v[90:93], v[142:145], v[208:211], v[90:93]
	v_mfma_f32_16x16x32_bf16 v[78:81], v[134:137], v[216:219], v[78:81]
	v_mfma_f32_16x16x32_bf16 v[74:77], v[142:145], v[216:219], v[74:77]
	s_setprio 0
	s_setprio 1
	v_mfma_f32_16x16x32_bf16 v[118:121], v[160:163], v[188:191], v[118:121]
	v_mfma_f32_16x16x32_bf16 v[114:117], v[180:183], v[188:191], v[114:117]
	v_mfma_f32_16x16x32_bf16 v[102:105], v[160:163], v[196:199], v[102:105]
	v_mfma_f32_16x16x32_bf16 v[98:101], v[180:183], v[196:199], v[98:101]
	v_mfma_f32_16x16x32_bf16 v[86:89], v[160:163], v[204:207], v[86:89]
	v_mfma_f32_16x16x32_bf16 v[82:85], v[180:183], v[204:207], v[82:85]
	v_mfma_f32_16x16x32_bf16 v[70:73], v[160:163], v[212:215], v[70:73]
	v_mfma_f32_16x16x32_bf16 v[66:69], v[180:183], v[212:215], v[66:69]
	v_mfma_f32_16x16x32_bf16 v[118:121], v[176:179], v[192:195], v[118:121]
	v_mfma_f32_16x16x32_bf16 v[114:117], v[184:187], v[192:195], v[114:117]
	v_mfma_f32_16x16x32_bf16 v[102:105], v[176:179], v[200:203], v[102:105]
	v_mfma_f32_16x16x32_bf16 v[98:101], v[184:187], v[200:203], v[98:101]
	v_mfma_f32_16x16x32_bf16 v[86:89], v[176:179], v[208:211], v[86:89]
	v_mfma_f32_16x16x32_bf16 v[82:85], v[184:187], v[208:211], v[82:85]
	v_mfma_f32_16x16x32_bf16 v[70:73], v[176:179], v[216:219], v[70:73]
	v_mfma_f32_16x16x32_bf16 v[66:69], v[184:187], v[216:219], v[66:69]
	s_setprio 0
	s_barrier
	s_add_i32 s24, s48, s30
	s_mov_b32 m0, s24
	ds_read_b128 v[188:191], v175 offset:49152
	ds_read_b128 v[192:195], v175 offset:50176
	ds_read_b128 v[196:199], v175 offset:51200
	ds_read_b128 v[200:203], v175 offset:52224
	ds_read_b128 v[204:207], v175 offset:53248
	ds_read_b128 v[208:211], v175 offset:54272
	ds_read_b128 v[212:215], v175 offset:55296
	ds_read_b128 v[216:219], v175 offset:56320
	global_load_lds_dwordx4 v0, s[98:99]
	s_add_i32 m0, s24, 0x2000
	s_add_u32 s22, s22, 0x40080
	s_addc_u32 s23, s23, 0
	s_add_i32 s24, s49, s30
	global_load_lds_dwordx4 v146, s[98:99]
	s_mov_b32 m0, s24
	s_nop 0
	global_load_lds_dwordx4 v0, s[22:23]
	s_add_i32 m0, s24, 0x2000
	s_nop 0
	global_load_lds_dwordx4 v146, s[22:23]
	s_mov_b32 m0, s41
	s_nop 0
	global_load_lds_dwordx4 v150, s[100:101]
	s_mov_b32 m0, s42
	s_nop 0
	global_load_lds_dwordx4 v148, s[100:101]
	s_waitcnt vmcnt(8)
	s_waitcnt lgkmcnt(0)
	s_barrier
	s_setprio 1
	s_waitcnt lgkmcnt(0)
	v_mfma_f32_16x16x32_bf16 v[62:65], v[130:133], v[188:191], v[62:65]
	v_mfma_f32_16x16x32_bf16 v[58:61], v[138:141], v[188:191], v[58:61]
	v_mfma_f32_16x16x32_bf16 v[46:49], v[130:133], v[196:199], v[46:49]
	v_mfma_f32_16x16x32_bf16 v[42:45], v[138:141], v[196:199], v[42:45]
	v_mfma_f32_16x16x32_bf16 v[30:33], v[130:133], v[204:207], v[30:33]
	v_mfma_f32_16x16x32_bf16 v[26:29], v[138:141], v[204:207], v[26:29]
	v_mfma_f32_16x16x32_bf16 v[14:17], v[130:133], v[212:215], v[14:17]
	v_mfma_f32_16x16x32_bf16 v[10:13], v[138:141], v[212:215], v[10:13]
	v_mfma_f32_16x16x32_bf16 v[62:65], v[134:137], v[192:195], v[62:65]
	v_mfma_f32_16x16x32_bf16 v[58:61], v[142:145], v[192:195], v[58:61]
	v_mfma_f32_16x16x32_bf16 v[46:49], v[134:137], v[200:203], v[46:49]
	v_mfma_f32_16x16x32_bf16 v[42:45], v[142:145], v[200:203], v[42:45]
	v_mfma_f32_16x16x32_bf16 v[30:33], v[134:137], v[208:211], v[30:33]
	v_mfma_f32_16x16x32_bf16 v[26:29], v[142:145], v[208:211], v[26:29]
	v_mfma_f32_16x16x32_bf16 v[14:17], v[134:137], v[216:219], v[14:17]
	v_mfma_f32_16x16x32_bf16 v[10:13], v[142:145], v[216:219], v[10:13]
	s_setprio 0
	s_setprio 1
	v_mfma_f32_16x16x32_bf16 v[54:57], v[160:163], v[188:191], v[54:57]
	v_mfma_f32_16x16x32_bf16 v[50:53], v[180:183], v[188:191], v[50:53]
	v_mfma_f32_16x16x32_bf16 v[38:41], v[160:163], v[196:199], v[38:41]
	v_mfma_f32_16x16x32_bf16 v[34:37], v[180:183], v[196:199], v[34:37]
	v_mfma_f32_16x16x32_bf16 v[22:25], v[160:163], v[204:207], v[22:25]
	v_mfma_f32_16x16x32_bf16 v[18:21], v[180:183], v[204:207], v[18:21]
	v_mfma_f32_16x16x32_bf16 v[6:9], v[160:163], v[212:215], v[6:9]
	v_mfma_f32_16x16x32_bf16 v[2:5], v[180:183], v[212:215], v[2:5]
	v_mfma_f32_16x16x32_bf16 v[54:57], v[176:179], v[192:195], v[54:57]
	v_mfma_f32_16x16x32_bf16 v[50:53], v[184:187], v[192:195], v[50:53]
	v_mfma_f32_16x16x32_bf16 v[38:41], v[176:179], v[200:203], v[38:41]
	v_mfma_f32_16x16x32_bf16 v[34:37], v[184:187], v[200:203], v[34:37]
	v_mfma_f32_16x16x32_bf16 v[22:25], v[176:179], v[208:211], v[22:25]
	v_mfma_f32_16x16x32_bf16 v[18:21], v[184:187], v[208:211], v[18:21]
	v_mfma_f32_16x16x32_bf16 v[6:9], v[176:179], v[216:219], v[6:9]
	v_mfma_f32_16x16x32_bf16 v[2:5], v[184:187], v[216:219], v[2:5]
	s_setprio 0
	s_barrier
	s_add_i32 s47, s47, 2
	s_add_u32 s20, s20, 0x100
	s_addc_u32 s21, s21, 0
	s_add_u32 s45, s45, 0x100
	s_addc_u32 s46, s46, 0
	s_cmp_gt_u32 s47, 13
	s_cbranch_scc0 .LBB0_1248
	s_and_b64 vcc, exec, s[6:7]
	s_cbranch_vccz .LBB0_1251
	s_barrier
